# v04 + la_job (HGRN2): flat->global prefetch loads, MFMA-stage LDS reads software-pipelined with counted waits
# speedup vs baseline: 1.0074x; 1.0019x over previous
.LBB0_781:
	s_lshl_b32 s16, s14, 7
	s_ashr_i32 s17, s16, 31
	s_lshl_b64 s[14:15], s[16:17], 2
	v_readlane_b32 s18, v255, 1
	s_add_u32 s20, s18, s14
	v_readlane_b32 s18, v254, 21
	s_addc_u32 s21, s18, s15
	s_and_b64 s[18:19], s[12:13], exec
	s_cselect_b32 s9, s9, s4
	s_lshl_b32 s9, s9, 5
	s_addk_i32 s9, 0x2000
	s_lshl_b32 s18, s4, 11
	s_and_b64 s[12:13], s[12:13], exec
	s_cselect_b32 s4, 32, 0x800
	s_cselect_b32 s72, s9, s18
	s_lshl_b64 s[12:13], s[16:17], 1
	v_readlane_b32 s9, v254, 52
	s_add_u32 s18, s9, s12
	v_readlane_b32 s9, v254, 49
	s_addc_u32 s19, s9, s13
	s_add_u32 s16, s20, s10
	s_addc_u32 s17, s21, s11
	v_lshlrev_b32_e32 v64, 4, v58
	global_load_dwordx4 v[38:41], v64, s[16:17]
	v_ashrrev_i32_e32 v68, 31, v59
	v_lshrrev_b32_e32 v1, 28, v68
	v_add_u32_e32 v1, v59, v1
	v_ashrrev_i32_e32 v83, 4, v1
	v_and_b32_e32 v1, -16, v1
	s_movk_i32 s9, 0x110
	v_sub_u32_e32 v67, v59, v1
	v_mad_u32_u24 v65, v95, s9, v64
	v_lshlrev_b32_e32 v1, 7, v95
	v_readlane_b32 s16, v252, 15
	v_lshlrev_b32_e32 v63, 3, v58
	v_sub_u32_e32 v1, v65, v1
	v_readlane_b32 s17, v252, 16
	v_sub_u32_e32 v60, v65, v63
	v_add_u32_e32 v66, 0x4400, v65
	v_add_u32_e32 v62, 0x8800, v1
	v_add_u32_e32 v61, 0x11400, v1
	s_mov_b32 s9, s17
	v_lshlrev_b32_e32 v1, 3, v67
	s_ashr_i32 s74, s72, 31
	s_ashr_i32 s17, s9, 31
	v_lshl_add_u32 v36, v83, 11, v1
	s_add_u32 s16, s9, s72
	v_mov_b32_e32 v37, v34
	s_addc_u32 s17, s17, s74
	s_sub_i32 s9, s4, s9
	v_lshl_add_u64 v[86:87], v[36:37], 1, s[18:19]
	v_mov_b32_e32 v36, v34
	s_min_i32 s9, s9, 64
	v_mov_b32_e32 v35, v34
	v_mov_b64_e32 v[44:45], v[36:37]
	v_cmp_gt_i32_e32 vcc, s9, v83
	v_mov_b64_e32 v[42:43], v[34:35]
	s_and_saveexec_b64 s[18:19], vcc
	s_cbranch_execz .LBB0_783
	s_lshl_b64 s[20:21], s[16:17], 12
	v_lshl_add_u64 v[42:43], v[86:87], 0, s[20:21]
	global_load_dwordx4 v[42:45], v[42:43], off
.LBB0_783:
	s_or_b64 exec, exec, s[18:19]
	v_add_u32_e32 v85, 32, v83
	v_mov_b64_e32 v[48:49], v[36:37]
	v_cmp_gt_i32_e32 vcc, s9, v85
	v_mov_b64_e32 v[46:47], v[34:35]
	s_and_saveexec_b64 s[18:19], vcc
	s_cbranch_execz .LBB0_785
	s_lshl_b64 s[20:21], s[16:17], 12
	v_lshl_add_u64 v[36:37], v[86:87], 0, s[20:21]
	v_add_co_u32_e32 v36, vcc, 0x20000, v36
	s_nop 1
	v_addc_co_u32_e32 v37, vcc, 0, v37, vcc
	global_load_dwordx4 v[46:49], v[36:37], off
.LBB0_785:
	s_or_b64 exec, exec, s[18:19]
	v_readlane_b32 s18, v255, 17
	v_lshlrev_b32_e32 v1, 3, v95
	s_add_u32 s18, s18, s12
	v_readlane_b32 s19, v255, 23
	v_ashrrev_i32_e32 v118, 4, v59
	s_addc_u32 s19, s19, s13
	v_lshl_or_b32 v36, v118, 11, v1
	v_mov_b32_e32 v37, v34
	v_lshl_add_u64 v[88:89], v[36:37], 1, s[18:19]
	v_mov_b32_e32 v36, v34
	v_mov_b32_e32 v35, v34
	v_mov_b64_e32 v[52:53], v[36:37]
	v_cmp_gt_i32_e32 vcc, s9, v118
	v_mov_b64_e32 v[50:51], v[34:35]
	s_and_saveexec_b64 s[18:19], vcc
	s_cbranch_execz .LBB0_787
	s_lshl_b64 s[20:21], s[16:17], 12
	v_lshl_add_u64 v[36:37], v[88:89], 0, s[20:21]
	global_load_dwordx4 v[50:53], v[36:37], off
.LBB0_787:
	s_or_b64 exec, exec, s[18:19]
	v_add_u32_e32 v119, 32, v118
	v_cmp_gt_i32_e32 vcc, s9, v119
	v_mov_b32_e32 v91, 0
	v_mov_b32_e32 v54, 0
	v_mov_b32_e32 v55, 0
	v_mov_b32_e32 v56, 0
	v_mov_b32_e32 v57, 0
	s_and_saveexec_b64 s[18:19], vcc
	s_cbranch_execz .LBB0_789
	s_lshl_b64 s[16:17], s[16:17], 12
	v_lshl_add_u64 v[36:37], v[88:89], 0, s[16:17]
	v_add_co_u32_e32 v36, vcc, 0x20000, v36
	s_nop 1
	v_addc_co_u32_e32 v37, vcc, 0, v37, vcc
	global_load_dwordx4 v[54:57], v[36:37], off
.LBB0_789:
	s_or_b64 exec, exec, s[18:19]
	s_ashr_i32 s9, s5, 31
	s_lshr_b32 s9, s9, 25
	s_add_i32 s9, s5, s9
	s_ashr_i32 s96, s9, 7
	v_readlane_b32 s9, v255, 9
	s_add_u32 s16, s9, s14
	v_readlane_b32 s9, v255, 13
	s_addc_u32 s17, s9, s15
	v_readlane_b32 s14, v252, 15
	v_lshrrev_b32_e32 v1, 25, v68
	v_readlane_b32 s15, v252, 16
	v_add_u32_e32 v1, v59, v1
	s_ashr_i32 s14, s15, 31
	v_and_b32_e32 v1, 0xffffff80, v1
	s_add_u32 s9, s15, s72
	v_sub_u32_e32 v36, v59, v1
	s_addc_u32 s14, s14, s74
	s_sub_i32 s15, s4, s15
	s_min_i32 s15, s15, 64
	s_lshl_b32 s75, s96, 4
	v_ashrrev_i32_e32 v37, 31, v36
	s_cmp_ge_i32 s75, s15
	v_lshl_add_u64 v[92:93], v[36:37], 2, s[16:17]
	s_cbranch_scc1 .LBB0_791
	s_ashr_i32 s17, s75, 31
	s_add_u32 s16, s9, s75
	s_addc_u32 s17, s14, s17
	s_lshl_b64 s[16:17], s[16:17], 13
	v_lshl_add_u64 v[68:69], v[92:93], 0, s[16:17]
	global_load_dword v91, v[68:69], off
.LBB0_791:
	s_or_b32 s76, s75, 1
	v_mov_b32_e32 v121, 0
	s_cmp_ge_i32 s76, s15
	v_mov_b32_e32 v120, 0
	s_cbranch_scc1 .LBB0_793
	s_ashr_i32 s17, s76, 31
	s_add_u32 s16, s9, s76
	s_addc_u32 s17, s14, s17
	s_lshl_b64 s[16:17], s[16:17], 13
	v_lshl_add_u64 v[68:69], v[92:93], 0, s[16:17]
	global_load_dword v120, v[68:69], off
.LBB0_793:
	s_or_b32 s77, s75, 2
	s_cmp_ge_i32 s77, s15
	s_cbranch_scc1 .LBB0_795
	s_ashr_i32 s17, s77, 31
	s_add_u32 s16, s9, s77
	s_addc_u32 s17, s14, s17
	s_lshl_b64 s[16:17], s[16:17], 13
	v_lshl_add_u64 v[68:69], v[92:93], 0, s[16:17]
	global_load_dword v121, v[68:69], off
.LBB0_795:
	s_or_b32 s78, s75, 3
	v_mov_b32_e32 v123, 0
	s_cmp_ge_i32 s78, s15
	v_mov_b32_e32 v122, 0
	s_cbranch_scc1 .LBB0_797
	s_ashr_i32 s17, s78, 31
	s_add_u32 s16, s9, s78
	s_addc_u32 s17, s14, s17
	s_lshl_b64 s[16:17], s[16:17], 13
	v_lshl_add_u64 v[68:69], v[92:93], 0, s[16:17]
	global_load_dword v122, v[68:69], off
.LBB0_797:
	s_or_b32 s79, s75, 4
	s_cmp_ge_i32 s79, s15
	s_cbranch_scc1 .LBB0_799
	s_ashr_i32 s17, s79, 31
	s_add_u32 s16, s9, s79
	s_addc_u32 s17, s14, s17
	s_lshl_b64 s[16:17], s[16:17], 13
	v_lshl_add_u64 v[68:69], v[92:93], 0, s[16:17]
	global_load_dword v123, v[68:69], off
.LBB0_799:
	s_or_b32 s80, s75, 5
	v_mov_b32_e32 v125, 0
	s_cmp_ge_i32 s80, s15
	v_mov_b32_e32 v124, 0
	s_cbranch_scc1 .LBB0_801
	s_ashr_i32 s17, s80, 31
	s_add_u32 s16, s9, s80
	s_addc_u32 s17, s14, s17
	s_lshl_b64 s[16:17], s[16:17], 13
	v_lshl_add_u64 v[68:69], v[92:93], 0, s[16:17]
	global_load_dword v124, v[68:69], off
.LBB0_801:
	s_or_b32 s81, s75, 6
	s_cmp_ge_i32 s81, s15
	s_cbranch_scc1 .LBB0_803
	s_ashr_i32 s17, s81, 31
	s_add_u32 s16, s9, s81
	s_addc_u32 s17, s14, s17
	s_lshl_b64 s[16:17], s[16:17], 13
	v_lshl_add_u64 v[68:69], v[92:93], 0, s[16:17]
	global_load_dword v125, v[68:69], off
.LBB0_803:
	s_or_b32 s82, s75, 7
	v_mov_b32_e32 v128, 0
	s_cmp_ge_i32 s82, s15
	v_mov_b32_e32 v126, 0
	s_cbranch_scc1 .LBB0_805
	s_ashr_i32 s17, s82, 31
	s_add_u32 s16, s9, s82
	s_addc_u32 s17, s14, s17
	s_lshl_b64 s[16:17], s[16:17], 13
	v_lshl_add_u64 v[68:69], v[92:93], 0, s[16:17]
	global_load_dword v126, v[68:69], off
.LBB0_805:
	s_or_b32 s83, s75, 8
	s_cmp_ge_i32 s83, s15
	s_cbranch_scc1 .LBB0_807
	s_ashr_i32 s17, s83, 31
	s_add_u32 s16, s9, s83
	s_addc_u32 s17, s14, s17
	s_lshl_b64 s[16:17], s[16:17], 13
	v_lshl_add_u64 v[68:69], v[92:93], 0, s[16:17]
	global_load_dword v128, v[68:69], off
.LBB0_807:
	s_or_b32 s84, s75, 9
	s_waitcnt lgkmcnt(0)
	v_mov_b32_e32 v134, 0
	s_cmp_ge_i32 s84, s15
	v_mov_b32_e32 v131, 0
	s_cbranch_scc1 .LBB0_809
	s_ashr_i32 s17, s84, 31
	s_add_u32 s16, s9, s84
	s_addc_u32 s17, s14, s17
	s_lshl_b64 s[16:17], s[16:17], 13
	v_lshl_add_u64 v[68:69], v[92:93], 0, s[16:17]
	global_load_dword v131, v[68:69], off
.LBB0_809:
	s_or_b32 s85, s75, 10
	s_cmp_ge_i32 s85, s15
	s_cbranch_scc1 .LBB0_811
	s_ashr_i32 s17, s85, 31
	s_add_u32 s16, s9, s85
	s_addc_u32 s17, s14, s17
	s_lshl_b64 s[16:17], s[16:17], 13
	v_lshl_add_u64 v[68:69], v[92:93], 0, s[16:17]
	global_load_dword v134, v[68:69], off
.LBB0_811:
	s_or_b32 s86, s75, 11
	v_mov_b32_e32 v147, 0
	s_cmp_ge_i32 s86, s15
	v_mov_b32_e32 v144, 0
	s_cbranch_scc1 .LBB0_813
	s_ashr_i32 s17, s86, 31
	s_add_u32 s16, s9, s86
	s_addc_u32 s17, s14, s17
	s_lshl_b64 s[16:17], s[16:17], 13
	v_lshl_add_u64 v[68:69], v[92:93], 0, s[16:17]
	global_load_dword v144, v[68:69], off
.LBB0_813:
	s_or_b32 s87, s75, 12
	s_cmp_ge_i32 s87, s15
	s_cbranch_scc1 .LBB0_815
	s_ashr_i32 s17, s87, 31
	s_add_u32 s16, s9, s87
	s_addc_u32 s17, s14, s17
	s_lshl_b64 s[16:17], s[16:17], 13
	v_lshl_add_u64 v[68:69], v[92:93], 0, s[16:17]
	global_load_dword v147, v[68:69], off
.LBB0_815:
	s_or_b32 s88, s75, 13
	v_mov_b32_e32 v175, 0
	s_cmp_ge_i32 s88, s15
	v_mov_b32_e32 v155, 0
	s_cbranch_scc1 .LBB0_817
	s_ashr_i32 s17, s88, 31
	s_add_u32 s16, s9, s88
	s_addc_u32 s17, s14, s17
	s_lshl_b64 s[16:17], s[16:17], 13
	v_lshl_add_u64 v[68:69], v[92:93], 0, s[16:17]
	global_load_dword v155, v[68:69], off
.LBB0_817:
	s_or_b32 s89, s75, 14
	s_cmp_ge_i32 s89, s15
	s_cbranch_scc1 .LBB0_819
	s_ashr_i32 s17, s89, 31
	s_add_u32 s16, s9, s89
	s_addc_u32 s17, s14, s17
	s_lshl_b64 s[16:17], s[16:17], 13
	v_lshl_add_u64 v[68:69], v[92:93], 0, s[16:17]
	global_load_dword v175, v[68:69], off
.LBB0_819:
	s_or_b32 s90, s75, 15
	s_ashr_i32 s91, s90, 31
	s_cmp_ge_i32 s90, s15
	v_mov_b32_e32 v176, 0
	s_cbranch_scc1 .LBB0_821
	s_add_u32 s16, s9, s90
	s_addc_u32 s17, s14, s91
	s_lshl_b64 s[14:15], s[16:17], 13
	v_lshl_add_u64 v[68:69], v[92:93], 0, s[14:15]
	global_load_dword v176, v[68:69], off

.LBB0_825:
	s_add_i32 s94, s94, 1
	s_cmp_lt_u32 s94, s92
	s_cselect_b64 s[0:1], -1, 0
	s_cmp_ge_u32 s94, s92
	s_waitcnt lgkmcnt(0)
	s_barrier
	s_cbranch_scc1 .LBB0_835
	s_mov_b32 s5, s8
	s_ashr_i32 s19, s5, 31
	s_add_u32 s18, s5, s72
	s_addc_u32 s19, s19, s74
	s_sub_i32 s5, s4, s5
	v_mov_b32_e32 v46, 0
	v_mov_b32_e32 v47, v34
	s_min_i32 s5, s5, 64
	v_mov_b32_e32 v48, v34
	v_mov_b32_e32 v49, v34
	v_mov_b64_e32 v[42:43], v[46:47]
	v_cmp_gt_i32_e32 vcc, s5, v83
	v_mov_b64_e32 v[44:45], v[48:49]
	s_and_saveexec_b64 s[20:21], vcc
	s_cbranch_execz .LBB0_828
	s_lshl_b64 s[62:63], s[18:19], 12
	v_lshl_add_u64 v[36:37], v[86:87], 0, s[62:63]
	global_load_dwordx4 v[42:45], v[36:37], off
.LBB0_828:
	s_or_b64 exec, exec, s[20:21]
	v_cmp_gt_i32_e32 vcc, s5, v85
	s_and_saveexec_b64 s[20:21], vcc
	s_cbranch_execz .LBB0_830
	s_lshl_b64 s[62:63], s[18:19], 12
	v_lshl_add_u64 v[36:37], v[86:87], 0, s[62:63]
	v_add_co_u32_e32 v36, vcc, 0x20000, v36
	s_nop 1
	v_addc_co_u32_e32 v37, vcc, 0, v37, vcc
	global_load_dwordx4 v[46:49], v[36:37], off
.LBB0_830:
	s_or_b64 exec, exec, s[20:21]
	v_mov_b32_e32 v36, v34
	v_mov_b32_e32 v37, v34
	v_mov_b32_e32 v35, v34
	v_mov_b64_e32 v[52:53], v[36:37]
	v_cmp_gt_i32_e32 vcc, s5, v118
	v_mov_b64_e32 v[50:51], v[34:35]
	s_and_saveexec_b64 s[20:21], vcc
	s_cbranch_execz .LBB0_832
	s_lshl_b64 s[62:63], s[18:19], 12
	v_lshl_add_u64 v[36:37], v[88:89], 0, s[62:63]
	global_load_dwordx4 v[50:53], v[36:37], off
.LBB0_832:
	s_or_b64 exec, exec, s[20:21]
	v_cmp_gt_i32_e32 vcc, s5, v119
	v_mov_b32_e32 v57, 0
	v_mov_b32_e32 v56, 0
	v_mov_b32_e32 v55, 0
	v_mov_b32_e32 v54, 0
	s_and_saveexec_b64 s[20:21], vcc
	s_cbranch_execz .LBB0_834
	s_lshl_b64 s[18:19], s[18:19], 12
	v_lshl_add_u64 v[36:37], v[88:89], 0, s[18:19]
	v_add_co_u32_e32 v36, vcc, 0x20000, v36
	s_nop 1
	v_addc_co_u32_e32 v37, vcc, 0, v37, vcc
	global_load_dwordx4 v[54:57], v[36:37], off

.LBB0_835:
	ds_read_b64_tr_b16 v[62:63], v159 offset:53248
	ds_read_b64_tr_b16 v[64:65], v159 offset:54336
	ds_read_b64_tr_b16 v[58:59], v159 offset:61952
	ds_read_b64_tr_b16 v[60:61], v159 offset:63040
	v_mov_b32_e32 v66, 0
	s_andn2_b64 vcc, exec, s[14:15]
	v_mov_b32_e32 v68, 0
	v_mov_b32_e32 v69, 0
	v_mov_b32_e32 v70, 0
	v_mov_b32_e32 v71, 0
	s_cbranch_vccnz .LBB0_837
	ds_read_b128 v[184:187], v172
	ds_read_b128 v[188:191], v173
	ds_read_b128 v[192:195], v172 offset:64
	ds_read_b128 v[196:199], v173 offset:64
	ds_read_b128 v[200:203], v172 offset:128
	ds_read_b128 v[204:207], v173 offset:128
	s_nop 0
	s_nop 0
	s_waitcnt lgkmcnt(6)
	s_waitcnt lgkmcnt(4)
	v_mfma_f32_16x16x32_bf16 v[68:71], v[184:187], v[188:191], 0
	s_nop 0
	s_nop 0
	s_nop 0
	s_waitcnt lgkmcnt(2)
	v_mfma_f32_16x16x32_bf16 v[68:71], v[192:195], v[196:199], v[68:71]
	s_nop 0
	s_nop 0
	s_nop 0
	s_waitcnt lgkmcnt(0)
	v_mfma_f32_16x16x32_bf16 v[68:71], v[200:203], v[204:207], v[68:71]
	ds_read_b128 v[72:75], v172 offset:192
	ds_read_b128 v[76:79], v173 offset:192
	s_nop 0
	s_waitcnt lgkmcnt(0)
	v_mfma_f32_16x16x32_bf16 v[68:71], v[72:75], v[76:79], v[68:71]
.LBB0_837:
	s_nop 7
	v_cndmask_b32_e64 v1, v68, 0, s[46:47]
	v_cndmask_b32_e64 v35, 0, v69, s[48:49]
	v_cndmask_b32_e64 v1, v1, v68, s[48:49]
	v_cndmask_b32_e64 v37, v70, 0, s[50:51]
	v_cndmask_b32_e64 v67, v71, 0, s[52:53]
	v_cvt_pk_bf16_f32 v36, v1, v35
	v_cvt_pk_bf16_f32 v37, v37, v67
	s_andn2_b64 vcc, exec, s[16:17]
	v_mov_b32_e32 v67, 0
	v_mov_b32_e32 v68, 0
	v_mov_b32_e32 v69, 0
	ds_write_b64 v160, v[36:37]
	s_cbranch_vccnz .LBB0_839
	ds_read_b128 v[184:187], v172 offset:4352
	ds_read_b128 v[188:191], v173
	ds_read_b128 v[192:195], v172 offset:4416
	ds_read_b128 v[196:199], v173 offset:64
	ds_read_b128 v[200:203], v172 offset:4480
	ds_read_b128 v[204:207], v173 offset:128
	s_nop 0
	s_nop 0
	s_waitcnt lgkmcnt(6)
	s_waitcnt lgkmcnt(4)
	v_mfma_f32_16x16x32_bf16 v[66:69], v[184:187], v[188:191], 0
	s_nop 0
	s_nop 0
	s_nop 0
	s_waitcnt lgkmcnt(2)
	v_mfma_f32_16x16x32_bf16 v[66:69], v[192:195], v[196:199], v[66:69]
	s_nop 0
	s_nop 0
	s_nop 0
	s_waitcnt lgkmcnt(0)
	v_mfma_f32_16x16x32_bf16 v[66:69], v[200:203], v[204:207], v[66:69]
	ds_read_b128 v[70:73], v172 offset:4544
	ds_read_b128 v[74:77], v173 offset:192
	s_nop 0
	s_waitcnt lgkmcnt(0)
	v_mfma_f32_16x16x32_bf16 v[66:69], v[70:73], v[74:77], v[66:69]
.LBB0_839:
	s_nop 7
	v_cndmask_b32_e64 v1, v66, 0, s[54:55]
	v_cndmask_b32_e64 v35, v67, 0, s[56:57]
	v_cndmask_b32_e64 v37, v68, 0, s[58:59]
	v_cndmask_b32_e64 v67, v69, 0, s[60:61]
	v_cvt_pk_bf16_f32 v66, v1, v35
	v_cvt_pk_bf16_f32 v67, v37, v67
	ds_write_b64 v161, v[66:67]
	ds_read_b128 v[184:187], v132
	ds_read_b128 v[188:191], v135
	s_nop 0
	s_nop 0
	v_add_u32_e32 v1, 0x1000, v162
	ds_read2_b64 v[192:195], v1 offset0:32 offset1:36
	ds_read2_b64 v[196:199], v162 offset1:4
	v_add_u32_e32 v35, 0x2000, v162
	ds_read2_b64 v[200:203], v35 offset0:64 offset1:68
	v_add_u32_e32 v37, 0x3000, v162
	ds_read2_b64 v[204:207], v37 offset0:96 offset1:100
	s_waitcnt lgkmcnt(7)
	s_waitcnt lgkmcnt(5)
	v_pk_mul_f32 v[68:69], v[4:5], v[186:187]
	ds_read_b128 v[208:211], v136
	v_pk_mul_f32 v[66:67], v[2:3], v[184:185]
	s_waitcnt lgkmcnt(5)
	v_pk_mul_f32 v[72:73], v[12:13], v[190:191]
	ds_read_b128 v[184:187], v137
	v_cvt_pk_bf16_f32 v66, v66, v67
	v_cvt_pk_bf16_f32 v67, v68, v69
	v_pk_mul_f32 v[68:69], v[10:11], v[188:189]
	s_nop 0
	v_cvt_pk_bf16_f32 v68, v68, v69
	v_cvt_pk_bf16_f32 v69, v72, v73
	s_nop 0
	s_nop 0
	s_nop 0
	s_nop 0
	s_waitcnt lgkmcnt(4)
	v_mfma_f32_16x16x32_bf16 v[70:73], v[66:69], v[196:199], 0
	s_sub_i32 s5, s8, 64
	s_add_u32 s18, s5, s72
	s_addc_u32 s19, 0, s74
	v_mfma_f32_16x16x32_bf16 v[74:77], v[66:69], v[192:195], 0
	ds_read2_b64 v[188:191], v162 offset0:8 offset1:12
	ds_read2_b64 v[192:195], v1 offset0:40 offset1:44
	v_mov_b32_e32 v36, 0
	v_cmp_gt_i32_e64 s[68:69], s9, v95
	v_or_b32_e32 v116, s18, v95
	s_waitcnt lgkmcnt(5)
	v_mfma_f32_16x16x32_bf16 v[78:81], v[66:69], v[200:203], 0
	ds_read2_b64 v[196:199], v35 offset0:72 offset1:76
	s_waitcnt lgkmcnt(5)
	v_mfma_f32_16x16x32_bf16 v[66:69], v[66:69], v[204:207], 0
	ds_read2_b64 v[200:203], v37 offset0:104 offset1:108
	s_nop 0
	s_nop 0
	s_nop 0
	s_waitcnt lgkmcnt(5)
	v_pk_mul_f32 v[106:107], v[8:9], v[210:211]
	ds_read_b128 v[204:207], v138
	v_pk_mul_f32 v[104:105], v[6:7], v[208:209]
	s_waitcnt lgkmcnt(5)
	v_pk_mul_f32 v[110:111], v[16:17], v[186:187]
	ds_read_b128 v[208:211], v139
	v_cvt_pk_bf16_f32 v104, v104, v105
	v_cvt_pk_bf16_f32 v105, v106, v107
	v_pk_mul_f32 v[106:107], v[14:15], v[184:185]
	s_nop 0
	v_cvt_pk_bf16_f32 v106, v106, v107
	v_cvt_pk_bf16_f32 v107, v110, v111
	s_nop 0
	s_nop 0
	s_waitcnt lgkmcnt(5)
	v_mfma_f32_16x16x32_bf16 v[70:73], v[104:107], v[188:191], v[70:73]
	ds_read2_b64 v[184:187], v162 offset0:16 offset1:20
	s_nop 0
	s_nop 0
	s_waitcnt lgkmcnt(5)
	v_mfma_f32_16x16x32_bf16 v[74:77], v[104:107], v[192:195], v[74:77]
	ds_read2_b64 v[188:191], v1 offset0:48 offset1:52
	s_nop 0
	s_nop 0
	s_waitcnt lgkmcnt(5)
	v_mfma_f32_16x16x32_bf16 v[78:81], v[104:107], v[196:199], v[78:81]
	ds_read2_b64 v[192:195], v35 offset0:80 offset1:84
	s_nop 0
	s_nop 0
	s_waitcnt lgkmcnt(5)
	v_mfma_f32_16x16x32_bf16 v[66:69], v[104:107], v[200:203], v[66:69]
	ds_read2_b64 v[196:199], v37 offset0:112 offset1:116
	s_nop 0
	s_nop 0
	s_nop 0
	s_waitcnt lgkmcnt(5)
	v_pk_mul_f32 v[106:107], v[20:21], v[206:207]
	ds_read_b128 v[200:203], v140
	v_pk_mul_f32 v[104:105], v[18:19], v[204:205]
	s_waitcnt lgkmcnt(5)
	v_pk_mul_f32 v[110:111], v[24:25], v[210:211]
	ds_read_b128 v[204:207], v141
	v_cvt_pk_bf16_f32 v104, v104, v105
	v_cvt_pk_bf16_f32 v105, v106, v107
	v_pk_mul_f32 v[106:107], v[22:23], v[208:209]
	s_nop 0
	v_cvt_pk_bf16_f32 v106, v106, v107
	v_cvt_pk_bf16_f32 v107, v110, v111
	s_nop 0
	s_nop 0
	s_waitcnt lgkmcnt(5)
	v_mfma_f32_16x16x32_bf16 v[70:73], v[104:107], v[184:187], v[70:73]
	ds_read2_b64 v[184:187], v162 offset0:24 offset1:28
	s_nop 0
	s_nop 0
	s_waitcnt lgkmcnt(5)
	v_mfma_f32_16x16x32_bf16 v[74:77], v[104:107], v[188:191], v[74:77]
	ds_read2_b64 v[188:191], v1 offset0:56 offset1:60
	s_nop 0
	s_nop 0
	s_waitcnt lgkmcnt(5)
	v_mfma_f32_16x16x32_bf16 v[78:81], v[104:107], v[192:195], v[78:81]
	ds_read2_b64 v[192:195], v35 offset0:88 offset1:92
	s_nop 0
	s_nop 0
	s_waitcnt lgkmcnt(5)
	v_mfma_f32_16x16x32_bf16 v[66:69], v[104:107], v[196:199], v[66:69]
	s_nop 0
	s_nop 0
	s_nop 0
	s_waitcnt lgkmcnt(4)
	v_pk_mul_f32 v[106:107], v[28:29], v[202:203]
	v_pk_mul_f32 v[104:105], v[26:27], v[200:201]
	s_waitcnt lgkmcnt(3)
	v_pk_mul_f32 v[110:111], v[32:33], v[206:207]
	v_cvt_pk_bf16_f32 v104, v104, v105
	v_cvt_pk_bf16_f32 v105, v106, v107
	v_pk_mul_f32 v[106:107], v[30:31], v[204:205]
	s_nop 0
	v_cvt_pk_bf16_f32 v106, v106, v107
	v_cvt_pk_bf16_f32 v107, v110, v111
	s_nop 0
	s_nop 0
	s_waitcnt lgkmcnt(2)
	v_mfma_f32_16x16x32_bf16 v[108:111], v[104:107], v[184:187], v[70:73]
	s_nop 2
	s_nop 0
	s_nop 0
	s_waitcnt lgkmcnt(1)
	v_mfma_f32_16x16x32_bf16 v[74:77], v[104:107], v[188:191], v[74:77]
	s_nop 0
	s_nop 0
	s_waitcnt lgkmcnt(0)
	v_mfma_f32_16x16x32_bf16 v[70:73], v[104:107], v[192:195], v[78:81]
	s_nop 2
	ds_read2_b64 v[78:81], v37 offset0:120 offset1:124
	s_nop 0
	s_waitcnt lgkmcnt(0)
	v_mfma_f32_16x16x32_bf16 v[66:69], v[104:107], v[78:81], v[66:69]
	s_barrier
	ds_read_b128 v[78:81], v174
	ds_read_b128 v[104:107], v174 offset:64
	s_waitcnt lgkmcnt(0)
	v_mfma_f32_16x16x32_bf16 v[78:81], v[62:65], v[78:81], v[108:111]
	v_mov_b32_e32 v37, 0
	v_mfma_f32_16x16x32_bf16 v[78:81], v[58:61], v[104:107], v[78:81]
	s_and_saveexec_b64 s[20:21], s[68:69]
	s_cbranch_execz .LBB0_841
	v_mov_b32_e32 v117, s19
	v_lshlrev_b64 v[36:37], 12, v[116:117]
	v_lshl_add_u64 v[36:37], v[102:103], 0, v[36:37]
	global_load_dwordx2 v[36:37], v[36:37], off

.LBB0_843:
	s_or_b64 exec, exec, s[20:21]
	s_waitcnt lgkmcnt(0)
	ds_read_b128 v[104:107], v174 offset:2304
	s_min_i32 s5, s9, 64
	v_cmp_gt_i32_e64 s[66:67], s5, v94
	v_mov_b32_e32 v114, 0
	v_or_b32_e32 v112, s18, v94
	s_waitcnt lgkmcnt(0)
	v_mfma_f32_16x16x32_bf16 v[74:77], v[62:65], v[104:107], v[74:77]
	ds_read_b128 v[104:107], v174 offset:2368
	v_mov_b32_e32 v115, 0
	s_waitcnt lgkmcnt(0)
	v_mfma_f32_16x16x32_bf16 v[74:77], v[58:61], v[104:107], v[74:77]
	s_and_saveexec_b64 s[20:21], s[66:67]
	s_cbranch_execz .LBB0_845
	v_mov_b32_e32 v113, s19
	v_lshlrev_b64 v[104:105], 12, v[112:113]
	v_lshl_add_u64 v[104:105], v[102:103], 0, v[104:105]
	global_load_dwordx2 v[114:115], v[104:105], off

.LBB0_847:
	s_or_b64 exec, exec, s[20:21]
	s_waitcnt lgkmcnt(0)
	ds_read_b128 v[104:107], v174 offset:4608
	v_cmp_gt_i32_e64 s[64:65], s5, v96
	v_mov_b32_e32 v110, 0
	v_lshl_add_u64 v[108:109], s[18:19], 0, v[96:97]
	v_mov_b32_e32 v111, 0
	s_waitcnt lgkmcnt(0)
	v_mfma_f32_16x16x32_bf16 v[70:73], v[62:65], v[104:107], v[70:73]
	ds_read_b128 v[104:107], v174 offset:4672
	s_waitcnt lgkmcnt(0)
	v_mfma_f32_16x16x32_bf16 v[70:73], v[58:61], v[104:107], v[70:73]
	s_and_saveexec_b64 s[20:21], s[64:65]
	s_cbranch_execz .LBB0_849
	v_lshlrev_b64 v[104:105], 12, v[108:109]
	v_lshl_add_u64 v[104:105], v[102:103], 0, v[104:105]
	global_load_dwordx2 v[110:111], v[104:105], off

.LBB0_851:
	s_or_b64 exec, exec, s[20:21]
	s_waitcnt lgkmcnt(0)
	ds_read_b128 v[104:107], v174 offset:6912
	v_cmp_gt_i32_e64 s[62:63], s5, v98
	s_waitcnt lgkmcnt(0)
	v_mfma_f32_16x16x32_bf16 v[66:69], v[62:65], v[104:107], v[66:69]
	ds_read_b128 v[104:107], v174 offset:6976
	s_waitcnt lgkmcnt(0)
	v_mfma_f32_16x16x32_bf16 v[66:69], v[58:61], v[104:107], v[66:69]
	v_mov_b32_e32 v106, 0
	v_lshl_add_u64 v[104:105], s[18:19], 0, v[98:99]
	v_mov_b32_e32 v107, 0
	s_and_saveexec_b64 s[20:21], s[62:63]
	s_cbranch_execz .LBB0_853
	v_lshlrev_b64 v[106:107], 12, v[104:105]
	v_lshl_add_u64 v[106:107], v[102:103], 0, v[106:107]
	global_load_dwordx2 v[106:107], v[106:107], off

.LBB0_872:
	s_add_u32 s0, s0, s90
	s_addc_u32 s1, s1, s91
	s_lshl_b64 s[0:1], s[0:1], 13
	v_lshl_add_u64 v[176:177], v[92:93], 0, s[0:1]
	global_load_dword v176, v[176:177], off
.LBB0_873:
	ds_read_b128 v[184:187], v133
	ds_read_b128 v[188:191], v163
	ds_read_b128 v[192:195], v163 offset:64
	ds_read_b128 v[196:199], v148
	ds_read_b128 v[200:203], v163 offset:2304
	ds_read_b128 v[204:207], v163 offset:2368
	s_nop 0
	s_waitcnt lgkmcnt(6)
	s_waitcnt lgkmcnt(5)
	v_pk_mul_f32 v[4:5], v[4:5], v[186:187]
	ds_read_b128 v[208:211], v149
	v_pk_mul_f32 v[2:3], v[2:3], v[184:185]
	s_nop 0
	s_nop 0
	s_waitcnt lgkmcnt(5)
	v_mfma_f32_16x16x32_bf16 v[2:5], v[188:191], v[62:65], v[2:5]
	ds_read_b128 v[184:187], v163 offset:4608
	s_nop 0
	s_nop 0
	s_waitcnt lgkmcnt(5)
	v_mfma_f32_16x16x32_bf16 v[2:5], v[192:195], v[58:61], v[2:5]
	ds_read_b128 v[188:191], v163 offset:4672
	s_nop 0
	s_nop 0
	s_waitcnt lgkmcnt(5)
	v_pk_mul_f32 v[12:13], v[12:13], v[198:199]
	ds_read_b128 v[192:195], v150
	v_pk_mul_f32 v[10:11], v[10:11], v[196:197]
	s_nop 0
	s_nop 0
	s_waitcnt lgkmcnt(5)
	v_mfma_f32_16x16x32_bf16 v[10:13], v[200:203], v[62:65], v[10:13]
	ds_read_b128 v[196:199], v163 offset:6912
	s_nop 0
	s_nop 0
	s_waitcnt lgkmcnt(5)
	v_mfma_f32_16x16x32_bf16 v[10:13], v[204:207], v[58:61], v[10:13]
	ds_read_b128 v[200:203], v163 offset:6976
	s_nop 0
	s_nop 0
	s_waitcnt lgkmcnt(5)
	v_pk_mul_f32 v[8:9], v[8:9], v[210:211]
	ds_read_b128 v[204:207], v151
	v_pk_mul_f32 v[6:7], v[6:7], v[208:209]
	s_nop 0
	s_nop 0
	s_waitcnt lgkmcnt(5)
	v_mfma_f32_16x16x32_bf16 v[6:9], v[184:187], v[62:65], v[6:9]
	ds_read_b128 v[184:187], v163 offset:9216
	s_nop 0
	s_nop 0
	s_waitcnt lgkmcnt(5)
	v_mfma_f32_16x16x32_bf16 v[6:9], v[188:191], v[58:61], v[6:9]
	ds_read_b128 v[188:191], v163 offset:9280
	s_nop 0
	s_nop 0
	s_waitcnt lgkmcnt(5)
	v_pk_mul_f32 v[16:17], v[16:17], v[194:195]
	ds_read_b128 v[208:211], v152
	v_pk_mul_f32 v[14:15], v[14:15], v[192:193]
	s_nop 0
	s_nop 0
	s_waitcnt lgkmcnt(5)
	v_mfma_f32_16x16x32_bf16 v[14:17], v[196:199], v[62:65], v[14:17]
	ds_read_b128 v[192:195], v163 offset:11520
	s_nop 0
	s_nop 0
	s_waitcnt lgkmcnt(5)
	v_mfma_f32_16x16x32_bf16 v[14:17], v[200:203], v[58:61], v[14:17]
	ds_read_b128 v[196:199], v163 offset:11584
	s_nop 0
	s_nop 0
	s_waitcnt lgkmcnt(5)
	v_pk_mul_f32 v[20:21], v[20:21], v[206:207]
	ds_read_b128 v[200:203], v153
	v_pk_mul_f32 v[18:19], v[18:19], v[204:205]
	s_nop 0
	s_nop 0
	s_waitcnt lgkmcnt(5)
	v_mfma_f32_16x16x32_bf16 v[18:21], v[184:187], v[62:65], v[18:21]
	ds_read_b128 v[184:187], v163 offset:13824
	s_nop 0
	s_nop 0
	s_waitcnt lgkmcnt(5)
	v_mfma_f32_16x16x32_bf16 v[18:21], v[188:191], v[58:61], v[18:21]
	ds_read_b128 v[188:191], v163 offset:13888
	s_nop 0
	s_nop 0
	s_waitcnt lgkmcnt(5)
	v_pk_mul_f32 v[24:25], v[24:25], v[210:211]
	ds_read_b128 v[204:207], v154
	v_pk_mul_f32 v[22:23], v[22:23], v[208:209]
	s_nop 0
	s_nop 0
	s_waitcnt lgkmcnt(5)
	v_mfma_f32_16x16x32_bf16 v[22:25], v[192:195], v[62:65], v[22:25]
	s_nop 0
	s_nop 0
	s_waitcnt lgkmcnt(4)
	v_mfma_f32_16x16x32_bf16 v[22:25], v[196:199], v[58:61], v[22:25]
	s_nop 0
	s_nop 0
	s_waitcnt lgkmcnt(3)
	v_pk_mul_f32 v[28:29], v[28:29], v[202:203]
	v_pk_mul_f32 v[26:27], v[26:27], v[200:201]
	s_nop 0
	s_nop 0
	s_waitcnt lgkmcnt(2)
	v_mfma_f32_16x16x32_bf16 v[26:29], v[184:187], v[62:65], v[26:29]
	s_nop 0
	s_nop 0
	s_waitcnt lgkmcnt(1)
	v_mfma_f32_16x16x32_bf16 v[26:29], v[188:191], v[58:61], v[26:29]
	s_nop 0
	s_nop 0
	s_waitcnt lgkmcnt(0)
	v_pk_mul_f32 v[32:33], v[32:33], v[206:207]
	v_pk_mul_f32 v[30:31], v[30:31], v[204:205]
	ds_read_b128 v[178:181], v163 offset:16128
	s_nop 0
	s_waitcnt lgkmcnt(0)
	v_mfma_f32_16x16x32_bf16 v[30:33], v[178:181], v[62:65], v[30:33]
	ds_read_b128 v[62:65], v163 offset:16192
	s_waitcnt lgkmcnt(0)
	s_barrier
	v_mfma_f32_16x16x32_bf16 v[30:33], v[62:65], v[58:61], v[30:33]
	s_and_saveexec_b64 s[20:21], s[68:69]
	s_cbranch_execz .LBB0_875
	v_add_u32_e32 v1, 0, v142
	v_add_u32_e32 v1, 0x14400, v1
	ds_read_b128 v[58:61], v1
	ds_read_b128 v[62:65], v1 offset:16
	s_mov_b32 s0, 0xf800000
	s_waitcnt lgkmcnt(0)
	v_mov_b32_e32 v178, v58
	v_mov_b32_e32 v179, v62
	v_mov_b32_e32 v62, v59
	v_pk_add_f32 v[58:59], v[178:179], v[62:63]
	v_mov_b32_e32 v62, v60
	v_mov_b32_e32 v63, v64
	v_mov_b32_e32 v64, v61
	v_pk_add_f32 v[60:61], v[62:63], v[64:65]
	s_waitcnt vmcnt(0)
	v_lshlrev_b32_e32 v62, 16, v37
	v_pk_add_f32 v[58:59], v[58:59], v[60:61]
	v_and_b32_e32 v63, 0xffff0000, v37
	v_add_f32_e32 v1, v58, v59
	v_fmamk_f32 v1, v1, 0x3c000000, v222
	v_cmp_gt_f32_e32 vcc, s0, v1
	v_mul_f32_e32 v35, 0x4f800000, v1
	s_nop 0
	v_cndmask_b32_e32 v1, v1, v35, vcc
	v_sqrt_f32_e32 v35, v1
	s_nop 0
	v_add_u32_e32 v58, -1, v35
	v_fma_f32 v59, -v58, v35, v1
	v_cmp_ge_f32_e64 s[0:1], 0, v59
	v_add_u32_e32 v59, 1, v35
	s_nop 0
	v_cndmask_b32_e64 v58, v35, v58, s[0:1]
	v_fma_f32 v35, -v59, v35, v1
	v_cmp_lt_f32_e64 s[0:1], 0, v35
	s_nop 1
	v_cndmask_b32_e64 v35, v58, v59, s[0:1]
	v_mul_f32_e32 v58, 0x37800000, v35
	v_cndmask_b32_e32 v35, v35, v58, vcc
	v_cmp_class_f32_e32 vcc, v1, v223
	s_nop 1
	v_cndmask_b32_e32 v1, v35, v1, vcc
	v_div_scale_f32 v35, s[0:1], v1, v1, 1.0
	v_rcp_f32_e32 v58, v35
	s_movk_i32 s0, 0x3000
	v_fma_f32 v59, -v35, v58, 1.0
	v_fmac_f32_e32 v58, v59, v58
	v_div_scale_f32 v59, vcc, 1.0, v1, 1.0
	v_mul_f32_e32 v60, v59, v58
	v_fma_f32 v61, -v35, v60, v59
	v_fmac_f32_e32 v60, v61, v58
	v_fma_f32 v35, -v35, v60, v59
	v_div_fmas_f32 v35, v35, v58, v60
	v_div_fixup_f32 v58, v35, v1, 1.0
	v_pk_mul_f32 v[60:61], v[80:81], v[58:59] op_sel_hi:[1,0]
	v_pk_mul_f32 v[58:59], v[78:79], v[58:59] op_sel_hi:[1,0]
	v_pk_mul_f32 v[60:61], v[40:41], v[60:61]
	v_pk_mul_f32 v[58:59], v[38:39], v[58:59]
	v_pk_mul_f32 v[60:61], v[60:61], v[62:63]
	s_nop 0
	v_cvt_pk_bf16_f32 v37, v60, v61
	v_lshlrev_b32_e32 v60, 16, v36
	v_and_b32_e32 v61, 0xffff0000, v36
	v_pk_mul_f32 v[58:59], v[58:59], v[60:61]
	s_nop 0
	v_cvt_pk_bf16_f32 v36, v58, v59
	v_mad_u64_u32 v[58:59], s[0:1], v116, s0, v[100:101]
	v_mad_i32_i24 v59, s19, v230, v59
	global_store_dwordx2 v[58:59], v[36:37], off

.LBB0_878:
	v_add_u32_e32 v1, 0, v143
	v_add_u32_e32 v1, 0x14400, v1
	ds_read_b128 v[58:61], v1
	ds_read_b128 v[62:65], v1 offset:16
	s_mov_b32 s0, 0xf800000
	s_waitcnt vmcnt(0) lgkmcnt(0)
	v_mov_b32_e32 v36, v58
	v_mov_b32_e32 v37, v62
	v_mov_b32_e32 v62, v59
	v_mov_b32_e32 v58, v60
	v_mov_b32_e32 v59, v64
	v_mov_b32_e32 v64, v61
	v_pk_add_f32 v[36:37], v[36:37], v[62:63]
	v_pk_add_f32 v[58:59], v[58:59], v[64:65]
	v_lshlrev_b32_e32 v60, 16, v115
	v_pk_add_f32 v[36:37], v[36:37], v[58:59]
	v_and_b32_e32 v61, 0xffff0000, v115
	v_add_f32_e32 v1, v36, v37
	v_fmamk_f32 v1, v1, 0x3c000000, v222
	v_cmp_gt_f32_e32 vcc, s0, v1
	v_mul_f32_e32 v35, 0x4f800000, v1
	s_nop 0
	v_cndmask_b32_e32 v1, v1, v35, vcc
	v_sqrt_f32_e32 v35, v1
	s_nop 0
	v_add_u32_e32 v36, -1, v35
	v_fma_f32 v37, -v36, v35, v1
	v_cmp_ge_f32_e64 s[0:1], 0, v37
	v_add_u32_e32 v37, 1, v35
	s_nop 0
	v_cndmask_b32_e64 v36, v35, v36, s[0:1]
	v_fma_f32 v35, -v37, v35, v1
	v_cmp_lt_f32_e64 s[0:1], 0, v35
	s_nop 1
	v_cndmask_b32_e64 v35, v36, v37, s[0:1]
	v_mul_f32_e32 v36, 0x37800000, v35
	v_cndmask_b32_e32 v35, v35, v36, vcc
	v_cmp_class_f32_e32 vcc, v1, v223
	s_nop 1
	v_cndmask_b32_e32 v1, v35, v1, vcc
	v_div_scale_f32 v35, s[0:1], v1, v1, 1.0
	v_rcp_f32_e32 v36, v35
	s_movk_i32 s0, 0x3000
	v_fma_f32 v37, -v35, v36, 1.0
	v_fmac_f32_e32 v36, v37, v36
	v_div_scale_f32 v37, vcc, 1.0, v1, 1.0
	v_mul_f32_e32 v58, v37, v36
	v_fma_f32 v59, -v35, v58, v37
	v_fmac_f32_e32 v58, v59, v36
	v_fma_f32 v35, -v35, v58, v37
	v_div_fmas_f32 v35, v35, v36, v58
	v_div_fixup_f32 v36, v35, v1, 1.0
	v_pk_mul_f32 v[58:59], v[76:77], v[36:37] op_sel_hi:[1,0]
	s_nop 0
	v_pk_mul_f32 v[58:59], v[40:41], v[58:59]
	s_nop 0
	v_pk_mul_f32 v[58:59], v[58:59], v[60:61]
	v_lshlrev_b32_e32 v60, 16, v114
	v_cvt_pk_bf16_f32 v37, v58, v59
	v_pk_mul_f32 v[58:59], v[74:75], v[36:37] op_sel_hi:[1,0]
	v_and_b32_e32 v61, 0xffff0000, v114
	v_pk_mul_f32 v[58:59], v[38:39], v[58:59]
	s_nop 0
	v_pk_mul_f32 v[58:59], v[58:59], v[60:61]
	s_nop 0
	v_cvt_pk_bf16_f32 v36, v58, v59
	v_mad_u64_u32 v[58:59], s[0:1], v112, s0, v[100:101]
	v_mad_i32_i24 v59, s19, v230, v59
	global_store_dwordx2 v[58:59], v[36:37], off
	s_or_b64 exec, exec, s[20:21]
	s_and_saveexec_b64 s[18:19], s[64:65]
	s_cbranch_execz .LBB0_877
.LBB0_879:
	v_add_u32_e32 v1, 0, v145
	v_add_u32_e32 v1, 0x14400, v1
	ds_read_b128 v[58:61], v1
	ds_read_b128 v[62:65], v1 offset:16
	s_mov_b32 s0, 0xf800000
	s_movk_i32 s5, 0x3000
	s_waitcnt vmcnt(0) lgkmcnt(0)
	v_mov_b32_e32 v36, v58
	v_mov_b32_e32 v37, v62
	v_mov_b32_e32 v62, v59
	v_mov_b32_e32 v58, v60
	v_mov_b32_e32 v59, v64
	v_mov_b32_e32 v64, v61
	v_pk_add_f32 v[36:37], v[36:37], v[62:63]
	v_pk_add_f32 v[58:59], v[58:59], v[64:65]
	v_lshlrev_b32_e32 v60, 16, v111
	v_pk_add_f32 v[36:37], v[36:37], v[58:59]
	v_and_b32_e32 v61, 0xffff0000, v111
	v_add_f32_e32 v1, v36, v37
	v_fmamk_f32 v1, v1, 0x3c000000, v222
	v_cmp_gt_f32_e32 vcc, s0, v1
	v_mul_f32_e32 v35, 0x4f800000, v1
	s_nop 0
	v_cndmask_b32_e32 v1, v1, v35, vcc
	v_sqrt_f32_e32 v35, v1
	s_nop 0
	v_add_u32_e32 v36, -1, v35
	v_fma_f32 v37, -v36, v35, v1
	v_cmp_ge_f32_e64 s[0:1], 0, v37
	v_add_u32_e32 v37, 1, v35
	s_nop 0
	v_cndmask_b32_e64 v36, v35, v36, s[0:1]
	v_fma_f32 v35, -v37, v35, v1
	v_cmp_lt_f32_e64 s[0:1], 0, v35
	s_nop 1
	v_cndmask_b32_e64 v35, v36, v37, s[0:1]
	v_mul_f32_e32 v36, 0x37800000, v35
	v_cndmask_b32_e32 v35, v35, v36, vcc
	v_cmp_class_f32_e32 vcc, v1, v223
	s_nop 1
	v_cndmask_b32_e32 v1, v35, v1, vcc
	v_div_scale_f32 v35, s[0:1], v1, v1, 1.0
	v_rcp_f32_e32 v36, v35
	s_nop 0
	v_fma_f32 v37, -v35, v36, 1.0
	v_fmac_f32_e32 v36, v37, v36
	v_div_scale_f32 v37, vcc, 1.0, v1, 1.0
	v_mul_f32_e32 v58, v37, v36
	v_fma_f32 v59, -v35, v58, v37
	v_fmac_f32_e32 v58, v59, v36
	v_fma_f32 v35, -v35, v58, v37
	v_div_fmas_f32 v35, v35, v36, v58
	v_div_fixup_f32 v36, v35, v1, 1.0
	v_pk_mul_f32 v[58:59], v[72:73], v[36:37] op_sel_hi:[1,0]
	s_nop 0
	v_pk_mul_f32 v[58:59], v[40:41], v[58:59]
	s_nop 0
	v_pk_mul_f32 v[58:59], v[58:59], v[60:61]
	v_lshlrev_b32_e32 v60, 16, v110
	v_cvt_pk_bf16_f32 v37, v58, v59
	v_pk_mul_f32 v[58:59], v[70:71], v[36:37] op_sel_hi:[1,0]
	v_and_b32_e32 v61, 0xffff0000, v110
	v_pk_mul_f32 v[58:59], v[38:39], v[58:59]
	s_nop 0
	v_pk_mul_f32 v[58:59], v[58:59], v[60:61]
	s_nop 0
	v_cvt_pk_bf16_f32 v36, v58, v59
	v_mad_u64_u32 v[58:59], s[0:1], v108, s5, v[100:101]
	v_mad_i32_i24 v59, v109, s5, v59
	global_store_dwordx2 v[58:59], v[36:37], off
	s_or_b64 exec, exec, s[18:19]
	s_and_saveexec_b64 s[18:19], s[62:63]
	s_cbranch_execz .LBB0_822
.LBB0_880:
	v_add_u32_e32 v1, 0, v146
	v_add_u32_e32 v1, 0x14400, v1
	ds_read_b128 v[58:61], v1
	ds_read_b128 v[62:65], v1 offset:16
	s_mov_b32 s0, 0xf800000
	s_movk_i32 s5, 0x3000
	s_waitcnt vmcnt(0) lgkmcnt(0)
	v_mov_b32_e32 v36, v58
	v_mov_b32_e32 v37, v62
	v_mov_b32_e32 v62, v59
	v_mov_b32_e32 v58, v60
	v_mov_b32_e32 v59, v64
	v_mov_b32_e32 v64, v61
	v_pk_add_f32 v[36:37], v[36:37], v[62:63]
	v_pk_add_f32 v[58:59], v[58:59], v[64:65]
	v_lshlrev_b32_e32 v60, 16, v107
	v_pk_add_f32 v[36:37], v[36:37], v[58:59]
	v_and_b32_e32 v61, 0xffff0000, v107
	v_add_f32_e32 v1, v36, v37
	v_fmamk_f32 v1, v1, 0x3c000000, v222
	v_cmp_gt_f32_e32 vcc, s0, v1
	v_mul_f32_e32 v35, 0x4f800000, v1
	s_nop 0
	v_cndmask_b32_e32 v1, v1, v35, vcc
	v_sqrt_f32_e32 v35, v1
	s_nop 0
	v_add_u32_e32 v36, -1, v35
	v_fma_f32 v37, -v36, v35, v1
	v_cmp_ge_f32_e64 s[0:1], 0, v37
	v_add_u32_e32 v37, 1, v35
	s_nop 0
	v_cndmask_b32_e64 v36, v35, v36, s[0:1]
	v_fma_f32 v35, -v37, v35, v1
	v_cmp_lt_f32_e64 s[0:1], 0, v35
	s_nop 1
	v_cndmask_b32_e64 v35, v36, v37, s[0:1]
	v_mul_f32_e32 v36, 0x37800000, v35
	v_cndmask_b32_e32 v35, v35, v36, vcc
	v_cmp_class_f32_e32 vcc, v1, v223
	s_nop 1
	v_cndmask_b32_e32 v1, v35, v1, vcc
	v_div_scale_f32 v35, s[0:1], v1, v1, 1.0
	v_rcp_f32_e32 v36, v35
	s_nop 0
	v_fma_f32 v37, -v35, v36, 1.0
	v_fmac_f32_e32 v36, v37, v36
	v_div_scale_f32 v37, vcc, 1.0, v1, 1.0
	v_mul_f32_e32 v58, v37, v36
	v_fma_f32 v59, -v35, v58, v37
	v_fmac_f32_e32 v58, v59, v36
	v_fma_f32 v35, -v35, v58, v37
	v_div_fmas_f32 v35, v35, v36, v58
	v_div_fixup_f32 v36, v35, v1, 1.0
	v_pk_mul_f32 v[58:59], v[68:69], v[36:37] op_sel_hi:[1,0]
	s_nop 0
	v_pk_mul_f32 v[58:59], v[40:41], v[58:59]
	s_nop 0
	v_pk_mul_f32 v[58:59], v[58:59], v[60:61]
	v_lshlrev_b32_e32 v60, 16, v106
	v_cvt_pk_bf16_f32 v37, v58, v59
	v_pk_mul_f32 v[58:59], v[66:67], v[36:37] op_sel_hi:[1,0]
	v_and_b32_e32 v61, 0xffff0000, v106
	v_pk_mul_f32 v[58:59], v[38:39], v[58:59]
	s_nop 0
	v_pk_mul_f32 v[58:59], v[58:59], v[60:61]
	s_nop 0
	v_cvt_pk_bf16_f32 v36, v58, v59
	v_mad_u64_u32 v[58:59], s[0:1], v104, s5, v[100:101]
	v_mad_i32_i24 v59, v105, s5, v59
	global_store_dwordx2 v[58:59], v[36:37], off
	s_branch .LBB0_822
.LBB0_881:
	s_add_u32 s20, s0, s75
	s_addc_u32 s21, s1, s97
	s_lshl_b64 s[20:21], s[20:21], 13
	s_waitcnt lgkmcnt(0)
	v_lshl_add_u64 v[90:91], v[92:93], 0, s[20:21]
	global_load_dword v91, v[90:91], off
	s_cmp_ge_i32 s76, s5
	s_cbranch_scc1 .LBB0_858
.LBB0_882:
	s_add_u32 s20, s0, s76
	s_addc_u32 s21, s1, s28
	s_lshl_b64 s[20:21], s[20:21], 13
	v_lshl_add_u64 v[120:121], v[92:93], 0, s[20:21]
	global_load_dword v120, v[120:121], off
	v_mov_b32_e32 v122, 0
	s_cmp_ge_i32 s77, s5
	v_mov_b32_e32 v121, 0
	s_cbranch_scc1 .LBB0_859
.LBB0_883:
	s_add_u32 s20, s0, s77
	s_addc_u32 s21, s1, s70
	s_lshl_b64 s[20:21], s[20:21], 13
	v_lshl_add_u64 v[124:125], v[92:93], 0, s[20:21]
	global_load_dword v121, v[124:125], off
	s_cmp_ge_i32 s78, s5
	s_cbranch_scc1 .LBB0_860
.LBB0_884:
	s_add_u32 s20, s0, s78
	s_addc_u32 s21, s1, s25
	s_lshl_b64 s[20:21], s[20:21], 13
	v_lshl_add_u64 v[122:123], v[92:93], 0, s[20:21]
	global_load_dword v122, v[122:123], off
	v_mov_b32_e32 v124, 0
	s_cmp_ge_i32 s79, s5
	v_mov_b32_e32 v123, 0
	s_cbranch_scc1 .LBB0_861
.LBB0_885:
	s_add_u32 s20, s0, s79
	s_addc_u32 s21, s1, s26
	s_lshl_b64 s[20:21], s[20:21], 13
	v_lshl_add_u64 v[176:177], v[92:93], 0, s[20:21]
	global_load_dword v123, v[176:177], off
	s_cmp_ge_i32 s80, s5
	s_cbranch_scc1 .LBB0_862
.LBB0_886:
	s_add_u32 s20, s0, s80
	s_addc_u32 s21, s1, s27
	s_lshl_b64 s[20:21], s[20:21], 13
	v_lshl_add_u64 v[124:125], v[92:93], 0, s[20:21]
	global_load_dword v124, v[124:125], off
	v_mov_b32_e32 v126, 0
	s_cmp_ge_i32 s81, s5
	v_mov_b32_e32 v125, 0
	s_cbranch_scc1 .LBB0_863
.LBB0_887:
	s_add_u32 s20, s0, s81
	s_addc_u32 s21, s1, s29
	s_lshl_b64 s[20:21], s[20:21], 13
	v_lshl_add_u64 v[176:177], v[92:93], 0, s[20:21]
	global_load_dword v125, v[176:177], off
	s_cmp_ge_i32 s82, s5
	s_cbranch_scc1 .LBB0_864
.LBB0_888:
	s_add_u32 s20, s0, s82
	s_addc_u32 s21, s1, s30
	s_lshl_b64 s[20:21], s[20:21], 13
	v_lshl_add_u64 v[176:177], v[92:93], 0, s[20:21]
	global_load_dword v126, v[176:177], off
	v_mov_b32_e32 v131, 0
	s_cmp_ge_i32 s83, s5
	v_mov_b32_e32 v128, 0
	s_cbranch_scc1 .LBB0_865
.LBB0_889:
	s_add_u32 s20, s0, s83
	s_addc_u32 s21, s1, s31
	s_lshl_b64 s[20:21], s[20:21], 13
	v_lshl_add_u64 v[176:177], v[92:93], 0, s[20:21]
	global_load_dword v128, v[176:177], off
	s_cmp_ge_i32 s84, s5
	s_cbranch_scc1 .LBB0_866
.LBB0_890:
	s_add_u32 s20, s0, s84
	s_addc_u32 s21, s1, s34
	s_lshl_b64 s[20:21], s[20:21], 13
	v_lshl_add_u64 v[176:177], v[92:93], 0, s[20:21]
	global_load_dword v131, v[176:177], off
	v_mov_b32_e32 v144, 0
	s_cmp_ge_i32 s85, s5
	v_mov_b32_e32 v134, 0
	s_cbranch_scc1 .LBB0_867
.LBB0_891:
	s_add_u32 s20, s0, s85
	s_addc_u32 s21, s1, s35
	s_lshl_b64 s[20:21], s[20:21], 13
	v_lshl_add_u64 v[176:177], v[92:93], 0, s[20:21]
	global_load_dword v134, v[176:177], off
	s_cmp_ge_i32 s86, s5
	s_cbranch_scc1 .LBB0_868
.LBB0_892:
	s_add_u32 s20, s0, s86
	s_addc_u32 s21, s1, s71
	s_lshl_b64 s[20:21], s[20:21], 13
	v_lshl_add_u64 v[176:177], v[92:93], 0, s[20:21]
	global_load_dword v144, v[176:177], off
	v_mov_b32_e32 v155, 0
	s_cmp_ge_i32 s87, s5
	v_mov_b32_e32 v147, 0
	s_cbranch_scc1 .LBB0_869
.LBB0_893:
	s_add_u32 s20, s0, s87
	s_addc_u32 s21, s1, s73
	s_lshl_b64 s[20:21], s[20:21], 13
	v_lshl_add_u64 v[176:177], v[92:93], 0, s[20:21]
	global_load_dword v147, v[176:177], off
	s_cmp_ge_i32 s88, s5
	s_cbranch_scc1 .LBB0_870
.LBB0_894:
	s_add_u32 s20, s0, s88
	s_addc_u32 s21, s1, s23
	s_lshl_b64 s[20:21], s[20:21], 13
	v_lshl_add_u64 v[176:177], v[92:93], 0, s[20:21]
	global_load_dword v155, v[176:177], off
	v_mov_b32_e32 v176, 0
	s_cmp_ge_i32 s89, s5
	v_mov_b32_e32 v175, 0
	s_cbranch_scc1 .LBB0_871
.LBB0_895:
	s_add_u32 s20, s0, s89
	s_addc_u32 s21, s1, s22
	s_lshl_b64 s[20:21], s[20:21], 13
	v_lshl_add_u64 v[178:179], v[92:93], 0, s[20:21]
	global_load_dword v175, v[178:179], off
	s_cmp_ge_i32 s90, s5
	s_cbranch_scc0 .LBB0_872
	s_branch .LBB0_873
